# grid barrier (8 in-loop sites) rewritten by hand: last XCD leader bumps all XCD generation words directly; other leaders spin on own XCD word; no top-level poll hop
# speedup vs baseline: 1.0698x; 1.0134x over previous
.LBB0_702:
	s_waitcnt vmcnt(0)
	s_waitcnt lgkmcnt(0)
	s_barrier
	s_mov_b64 s[4:5], exec
	v_readlane_b32 s6, v246, 1
	v_readlane_b32 s7, v246, 2
	s_and_b64 s[6:7], s[4:5], s[6:7]
	s_mov_b64 exec, s[6:7]
	s_cbranch_execz .Lgb0_done
	s_waitcnt vmcnt(0) expcnt(0) lgkmcnt(0)
	global_atomic_add v2, v[182:183], v189, off sc0
	v_cvt_f32_u32_e32 v0, v186
	v_sub_u32_e32 v3, 0, v186
	v_rcp_iflag_f32_e32 v0, v0
	s_nop 0
	v_mul_f32_e32 v0, 0x4f7ffffe, v0
	v_cvt_u32_f32_e32 v0, v0
	v_mul_lo_u32 v3, v3, v0
	v_mul_hi_u32 v3, v0, v3
	v_add_u32_e32 v0, v0, v3
	s_waitcnt vmcnt(0)
	v_mul_hi_u32 v0, v2, v0
	v_mul_lo_u32 v3, v0, v186
	v_sub_u32_e32 v3, v2, v3
	v_cmp_ge_u32_e32 vcc, v3, v186
	v_add_u32_e32 v4, 1, v0
	s_nop 0
	v_cndmask_b32_e32 v0, v0, v4, vcc
	v_sub_u32_e32 v4, v3, v186
	v_cndmask_b32_e32 v3, v3, v4, vcc
	v_cmp_ge_u32_e32 vcc, v3, v186
	v_add_u32_e32 v3, 1, v0
	v_add_u32_e32 v4, 1, v2
	v_cndmask_b32_e32 v0, v0, v3, vcc
	v_add_u32_e32 v3, 1, v0
	v_mul_lo_u32 v3, v3, v186
	v_cmp_eq_u32_e32 vcc, v4, v3
	v_readfirstlane_b32 s10, v0
	s_mov_b32 s0, 0
	s_cbranch_vccz .Lgb0_spin
	buffer_wbl2 sc1
	s_waitcnt vmcnt(0)
	v_readlane_b32 s8, v246, 53
	v_readlane_b32 s9, v246, 54
	s_nop 4
	global_atomic_add v2, v1, v189, s[8:9] sc0
	v_cvt_f32_u32_e32 v0, v188
	v_sub_u32_e32 v3, 0, v188
	v_rcp_iflag_f32_e32 v0, v0
	s_nop 0
	v_mul_f32_e32 v0, 0x4f7ffffe, v0
	v_cvt_u32_f32_e32 v0, v0
	v_mul_lo_u32 v3, v3, v0
	v_mul_hi_u32 v3, v0, v3
	v_add_u32_e32 v0, v0, v3
	s_waitcnt vmcnt(0)
	v_mul_hi_u32 v0, v2, v0
	v_mul_lo_u32 v3, v0, v188
	v_sub_u32_e32 v3, v2, v3
	v_cmp_ge_u32_e32 vcc, v3, v188
	v_add_u32_e32 v4, 1, v0
	s_nop 0
	v_cndmask_b32_e32 v0, v0, v4, vcc
	v_sub_u32_e32 v4, v3, v188
	v_cndmask_b32_e32 v3, v3, v4, vcc
	v_cmp_ge_u32_e32 vcc, v3, v188
	v_add_u32_e32 v3, 1, v0
	v_add_u32_e32 v4, 1, v2
	v_cndmask_b32_e32 v0, v0, v3, vcc
	v_add_u32_e32 v3, 1, v0
	v_mul_lo_u32 v3, v3, v188
	v_cmp_eq_u32_e32 vcc, v4, v3
	s_cbranch_vccz .Lgb0_spin
	s_add_u32 s8, s94, 0x2400
	s_addc_u32 s9, s95, 0
	global_atomic_add v1, v189, s[8:9]
	global_atomic_add v1, v189, s[8:9] offset:256
	global_atomic_add v1, v189, s[8:9] offset:512
	global_atomic_add v1, v189, s[8:9] offset:768
	global_atomic_add v1, v189, s[8:9] offset:1024
	global_atomic_add v1, v189, s[8:9] offset:1280
	global_atomic_add v1, v189, s[8:9] offset:1536
	global_atomic_add v1, v189, s[8:9] offset:1792
	global_atomic_add v1, v189, s[8:9] offset:2048
	global_atomic_add v1, v189, s[8:9] offset:2304
	global_atomic_add v1, v189, s[8:9] offset:2560
	global_atomic_add v1, v189, s[8:9] offset:2816
	global_atomic_add v1, v189, s[8:9] offset:3072
	global_atomic_add v1, v189, s[8:9] offset:3328
	global_atomic_add v1, v189, s[8:9] offset:3584
	global_atomic_add v1, v189, s[8:9] offset:3840
	v_readlane_b32 s6, v246, 55
	v_readlane_b32 s7, v246, 56
	s_nop 4
	global_atomic_add v1, v189, s[6:7]
	s_branch .Lgb0_acq
.Lgb0_spin:
	global_load_dword v2, v[184:185], off sc1
	s_add_i32 s0, s0, 1
	s_waitcnt vmcnt(0)
	v_cmp_ne_u32_e32 vcc, s10, v2
	s_cbranch_vccnz .Lgb0_acq
	s_sleep 1
	s_cmp_lt_u32 s0, 0x8000
	s_cbranch_scc1 .Lgb0_spin
.Lgb0_acq:
	buffer_inv sc1
	s_waitcnt vmcnt(0)

.LBB0_917:
	s_waitcnt vmcnt(0)
	s_barrier
	s_mov_b64 s[4:5], exec
	v_readlane_b32 s6, v246, 1
	v_readlane_b32 s7, v246, 2
	s_and_b64 s[6:7], s[4:5], s[6:7]
	s_mov_b64 exec, s[6:7]
	s_cbranch_execz .Lgb1_done
	s_waitcnt vmcnt(0) expcnt(0) lgkmcnt(0)
	global_atomic_add v2, v[182:183], v189, off sc0
	v_cvt_f32_u32_e32 v0, v186
	v_sub_u32_e32 v3, 0, v186
	v_rcp_iflag_f32_e32 v0, v0
	s_nop 0
	v_mul_f32_e32 v0, 0x4f7ffffe, v0
	v_cvt_u32_f32_e32 v0, v0
	v_mul_lo_u32 v3, v3, v0
	v_mul_hi_u32 v3, v0, v3
	v_add_u32_e32 v0, v0, v3
	s_waitcnt vmcnt(0)
	v_mul_hi_u32 v0, v2, v0
	v_mul_lo_u32 v3, v0, v186
	v_sub_u32_e32 v3, v2, v3
	v_cmp_ge_u32_e32 vcc, v3, v186
	v_add_u32_e32 v4, 1, v0
	s_nop 0
	v_cndmask_b32_e32 v0, v0, v4, vcc
	v_sub_u32_e32 v4, v3, v186
	v_cndmask_b32_e32 v3, v3, v4, vcc
	v_cmp_ge_u32_e32 vcc, v3, v186
	v_add_u32_e32 v3, 1, v0
	v_add_u32_e32 v4, 1, v2
	v_cndmask_b32_e32 v0, v0, v3, vcc
	v_add_u32_e32 v3, 1, v0
	v_mul_lo_u32 v3, v3, v186
	v_cmp_eq_u32_e32 vcc, v4, v3
	v_readfirstlane_b32 s10, v0
	s_mov_b32 s0, 0
	s_cbranch_vccz .Lgb1_spin
	buffer_wbl2 sc1
	s_waitcnt vmcnt(0)
	v_readlane_b32 s8, v246, 53
	v_readlane_b32 s9, v246, 54
	s_nop 4
	global_atomic_add v2, v1, v189, s[8:9] sc0
	v_cvt_f32_u32_e32 v0, v188
	v_sub_u32_e32 v3, 0, v188
	v_rcp_iflag_f32_e32 v0, v0
	s_nop 0
	v_mul_f32_e32 v0, 0x4f7ffffe, v0
	v_cvt_u32_f32_e32 v0, v0
	v_mul_lo_u32 v3, v3, v0
	v_mul_hi_u32 v3, v0, v3
	v_add_u32_e32 v0, v0, v3
	s_waitcnt vmcnt(0)
	v_mul_hi_u32 v0, v2, v0
	v_mul_lo_u32 v3, v0, v188
	v_sub_u32_e32 v3, v2, v3
	v_cmp_ge_u32_e32 vcc, v3, v188
	v_add_u32_e32 v4, 1, v0
	s_nop 0
	v_cndmask_b32_e32 v0, v0, v4, vcc
	v_sub_u32_e32 v4, v3, v188
	v_cndmask_b32_e32 v3, v3, v4, vcc
	v_cmp_ge_u32_e32 vcc, v3, v188
	v_add_u32_e32 v3, 1, v0
	v_add_u32_e32 v4, 1, v2
	v_cndmask_b32_e32 v0, v0, v3, vcc
	v_add_u32_e32 v3, 1, v0
	v_mul_lo_u32 v3, v3, v188
	v_cmp_eq_u32_e32 vcc, v4, v3
	s_cbranch_vccz .Lgb1_spin
	s_add_u32 s8, s94, 0x2400
	s_addc_u32 s9, s95, 0
	global_atomic_add v1, v189, s[8:9]
	global_atomic_add v1, v189, s[8:9] offset:256
	global_atomic_add v1, v189, s[8:9] offset:512
	global_atomic_add v1, v189, s[8:9] offset:768
	global_atomic_add v1, v189, s[8:9] offset:1024
	global_atomic_add v1, v189, s[8:9] offset:1280
	global_atomic_add v1, v189, s[8:9] offset:1536
	global_atomic_add v1, v189, s[8:9] offset:1792
	global_atomic_add v1, v189, s[8:9] offset:2048
	global_atomic_add v1, v189, s[8:9] offset:2304
	global_atomic_add v1, v189, s[8:9] offset:2560
	global_atomic_add v1, v189, s[8:9] offset:2816
	global_atomic_add v1, v189, s[8:9] offset:3072
	global_atomic_add v1, v189, s[8:9] offset:3328
	global_atomic_add v1, v189, s[8:9] offset:3584
	global_atomic_add v1, v189, s[8:9] offset:3840
	v_readlane_b32 s6, v246, 55
	v_readlane_b32 s7, v246, 56
	s_nop 4
	global_atomic_add v1, v189, s[6:7]
	s_branch .Lgb1_acq

.LBB0_1180:
	s_or_b64 exec, exec, s[34:35]
	s_waitcnt vmcnt(0)
	s_barrier
	s_mov_b64 s[4:5], exec
	v_readlane_b32 s6, v246, 1
	v_readlane_b32 s7, v246, 2
	s_and_b64 s[6:7], s[4:5], s[6:7]
	s_mov_b64 exec, s[6:7]
	s_cbranch_execz .Lgb4_done
	s_waitcnt vmcnt(0) expcnt(0) lgkmcnt(0)
	global_atomic_add v2, v[182:183], v189, off sc0
	v_cvt_f32_u32_e32 v0, v186
	v_sub_u32_e32 v3, 0, v186
	v_rcp_iflag_f32_e32 v0, v0
	s_nop 0
	v_mul_f32_e32 v0, 0x4f7ffffe, v0
	v_cvt_u32_f32_e32 v0, v0
	v_mul_lo_u32 v3, v3, v0
	v_mul_hi_u32 v3, v0, v3
	v_add_u32_e32 v0, v0, v3
	s_waitcnt vmcnt(0)
	v_mul_hi_u32 v0, v2, v0
	v_mul_lo_u32 v3, v0, v186
	v_sub_u32_e32 v3, v2, v3
	v_cmp_ge_u32_e32 vcc, v3, v186
	v_add_u32_e32 v4, 1, v0
	s_nop 0
	v_cndmask_b32_e32 v0, v0, v4, vcc
	v_sub_u32_e32 v4, v3, v186
	v_cndmask_b32_e32 v3, v3, v4, vcc
	v_cmp_ge_u32_e32 vcc, v3, v186
	v_add_u32_e32 v3, 1, v0
	v_add_u32_e32 v4, 1, v2
	v_cndmask_b32_e32 v0, v0, v3, vcc
	v_add_u32_e32 v3, 1, v0
	v_mul_lo_u32 v3, v3, v186
	v_cmp_eq_u32_e32 vcc, v4, v3
	v_readfirstlane_b32 s10, v0
	s_mov_b32 s0, 0
	s_cbranch_vccz .Lgb4_spin
	buffer_wbl2 sc1
	s_waitcnt vmcnt(0)
	v_readlane_b32 s8, v246, 53
	v_readlane_b32 s9, v246, 54
	s_nop 4
	global_atomic_add v2, v1, v189, s[8:9] sc0
	v_cvt_f32_u32_e32 v0, v188
	v_sub_u32_e32 v3, 0, v188
	v_rcp_iflag_f32_e32 v0, v0
	s_nop 0
	v_mul_f32_e32 v0, 0x4f7ffffe, v0
	v_cvt_u32_f32_e32 v0, v0
	v_mul_lo_u32 v3, v3, v0
	v_mul_hi_u32 v3, v0, v3
	v_add_u32_e32 v0, v0, v3
	s_waitcnt vmcnt(0)
	v_mul_hi_u32 v0, v2, v0
	v_mul_lo_u32 v3, v0, v188
	v_sub_u32_e32 v3, v2, v3
	v_cmp_ge_u32_e32 vcc, v3, v188
	v_add_u32_e32 v4, 1, v0
	s_nop 0
	v_cndmask_b32_e32 v0, v0, v4, vcc
	v_sub_u32_e32 v4, v3, v188
	v_cndmask_b32_e32 v3, v3, v4, vcc
	v_cmp_ge_u32_e32 vcc, v3, v188
	v_add_u32_e32 v3, 1, v0
	v_add_u32_e32 v4, 1, v2
	v_cndmask_b32_e32 v0, v0, v3, vcc
	v_add_u32_e32 v3, 1, v0
	v_mul_lo_u32 v3, v3, v188
	v_cmp_eq_u32_e32 vcc, v4, v3
	s_cbranch_vccz .Lgb4_spin
	s_add_u32 s8, s94, 0x2400
	s_addc_u32 s9, s95, 0
	global_atomic_add v1, v189, s[8:9]
	global_atomic_add v1, v189, s[8:9] offset:256
	global_atomic_add v1, v189, s[8:9] offset:512
	global_atomic_add v1, v189, s[8:9] offset:768
	global_atomic_add v1, v189, s[8:9] offset:1024
	global_atomic_add v1, v189, s[8:9] offset:1280
	global_atomic_add v1, v189, s[8:9] offset:1536
	global_atomic_add v1, v189, s[8:9] offset:1792
	global_atomic_add v1, v189, s[8:9] offset:2048
	global_atomic_add v1, v189, s[8:9] offset:2304
	global_atomic_add v1, v189, s[8:9] offset:2560
	global_atomic_add v1, v189, s[8:9] offset:2816
	global_atomic_add v1, v189, s[8:9] offset:3072
	global_atomic_add v1, v189, s[8:9] offset:3328
	global_atomic_add v1, v189, s[8:9] offset:3584
	global_atomic_add v1, v189, s[8:9] offset:3840
	v_readlane_b32 s6, v246, 55
	v_readlane_b32 s7, v246, 56
	s_nop 4
	global_atomic_add v1, v189, s[6:7]
	s_branch .Lgb4_acq
